# GEMM phase prologue de-serialised: all 7 half-tile stages issued before the first wait (vmcnt(6)) instead of 4 + wait + 3
# speedup vs baseline: 1.0176x; 1.0176x over previous
; #define PG8_STAGE(bufoff, gbase, voff) do { _Pragma("unroll") for (int _i = 0; _i < 2; ++_i) \
;         __builtin_amdgcn_global_load_lds((const unsigned*)((const char*)(gbase) + (voff)[_i]), (LAS unsigned*)(lds + (bufoff) + ldsw + _i * 8192), 16, 0, 0); } while (0)
; #define PG8_WAIT_V(n) asm volatile("s_waitcnt vmcnt(" #n ")" ::: "memory")
; #define PG8_BAR __builtin_amdgcn_s_barrier()
; template <class Epi>
; __device__ __forceinline__ void gemm_phase(LAS unsigned char* lds, const Gemm g, const StaticOrder& S, const Epi& E) {
;     ...
;     PG8_STAGE(PG8_SB(0, 0), cB, voffB); PG8_STAGE(PG8_SA(0, 0), cA, voffA); PG8_STAGE(PG8_SB(0, 1), cB + hstepB, voffB); PG8_STAGE(PG8_SA(0, 1), cA + hstepA, voffA);
;     if (wr == 1) PG8_BAR;
;     PG8_WAIT_V(4); PG8_BAR;
;     PG8_STAGE(PG8_SB(1, 0), cB + kstep, voffB); PG8_STAGE(PG8_SA(1, 0), cA + kstep, voffA); PG8_STAGE(PG8_SB(1, 1), cB + hstepB + kstep, voffB);
;     PG8_WAIT_V(6); PG8_BAR;
.LBB0_133:
	s_and_b32 s4, s4, 3
	s_lshl_b32 s41, s1, 6
	s_lshl_b32 s14, s1, 13
	s_lshl_b32 s42, s4, 5
	s_lshl_b32 s15, s4, 12
	s_add_u32 s4, s24, 0x4000
	v_mov_b32_e32 v129, v153
	s_addc_u32 s5, s25, 0
	s_add_i32 m0, s37, 0x18000
	v_lshl_add_u64 v[2:3], s[4:5], 0, v[128:129]
	v_mov_b32_e32 v131, v153
	global_load_lds_dwordx4 v[2:3], off
	s_add_i32 m0, s37, 0x1a000
	v_lshl_add_u64 v[2:3], s[4:5], 0, v[130:131]
	s_add_u32 s4, s22, 0x4000
	s_addc_u32 s5, s23, 0
	s_add_i32 s43, s37, 0x8000
	global_load_lds_dwordx4 v[2:3], off
	v_lshl_add_u64 v[2:3], s[4:5], 0, v[128:129]
	s_mov_b32 m0, s43
	s_add_i32 s44, s37, 0xa000
	global_load_lds_dwordx4 v[2:3], off
	v_lshl_add_u64 v[2:3], s[4:5], 0, v[130:131]
	s_add_u32 s4, s24, 0x84000
	s_mov_b32 m0, s44
	s_addc_u32 s5, s25, 0
	global_load_lds_dwordx4 v[2:3], off
	s_add_i32 m0, s37, 0x1c000
	v_lshl_add_u64 v[2:3], s[4:5], 0, v[128:129]
	global_load_lds_dwordx4 v[2:3], off
	v_lshl_add_u64 v[2:3], s[4:5], 0, v[130:131]
	s_add_i32 m0, s37, 0x1e000
	s_sext_i32_i8 s21, s0
	global_load_lds_dwordx4 v[2:3], off
	s_lshl_b32 s0, s1, 3
	s_bfe_u32 s45, s31, 0x10006
	s_and_b32 s0, s0, 8
	s_or_b32 s0, s0, s45
	s_waitcnt vmcnt(6)
	s_barrier
	s_waitcnt vmcnt(6)
	s_barrier
	s_lshl_b32 s46, s0, 10
	s_load_dword s0, s[84:85], 0x0
	v_and_b32_e32 v132, 15, v0
	v_and_b32_e32 v133, 48, v0
	v_lshlrev_b32_e32 v0, 2, v0
	v_lshl_or_b32 v1, v132, 6, v133
	v_and_b32_e32 v0, 32, v0
	v_bitop3_b32 v2, v1, s14, v0 bitop3:0xde
	v_bitop3_b32 v134, v1, s15, v0 bitop3:0xde
	s_waitcnt lgkmcnt(0)
	s_ashr_i32 s47, s0, 31
	s_mov_b32 s48, 0
	v_add_u32_e32 v135, 0, v2

; #define PG8_STAGE(bufoff, gbase, voff) do { _Pragma("unroll") for (int _i = 0; _i < 2; ++_i) \
;         __builtin_amdgcn_global_load_lds((const unsigned*)((const char*)(gbase) + (voff)[_i]), (LAS unsigned*)(lds + (bufoff) + ldsw + _i * 8192), 16, 0, 0); } while (0)
; #define PG8_WAIT_V(n) asm volatile("s_waitcnt vmcnt(" #n ")" ::: "memory")
; #define PG8_BAR __builtin_amdgcn_s_barrier()
; template <class Epi>
; __device__ __forceinline__ void gemm_phase(LAS unsigned char* lds, const Gemm g, const StaticOrder& S, const Epi& E) {
;     ...
;     PG8_STAGE(PG8_SB(0, 0), cB, voffB); PG8_STAGE(PG8_SA(0, 0), cA, voffA); PG8_STAGE(PG8_SB(0, 1), cB + hstepB, voffB); PG8_STAGE(PG8_SA(0, 1), cA + hstepA, voffA);
;     if (wr == 1) PG8_BAR;
;     PG8_WAIT_V(4); PG8_BAR;
;     PG8_STAGE(PG8_SB(1, 0), cB + kstep, voffB); PG8_STAGE(PG8_SA(1, 0), cA + kstep, voffA); PG8_STAGE(PG8_SB(1, 1), cB + hstepB + kstep, voffB);
;     PG8_WAIT_V(6); PG8_BAR;
.LBB0_174:
	s_lshl_b32 s6, s6, 5
	s_and_b32 s21, s6, 0x60
	s_lshl_b32 s37, s7, 6
	s_lshl_b32 s20, s7, 13
	s_lshl_b32 s26, s21, 7
	s_add_u32 s6, s22, 0x4000
	s_addc_u32 s7, s23, 0
	s_add_i32 m0, s33, 0x18000
	v_lshl_add_u64 v[2:3], s[6:7], 0, v[152:153]
	v_mov_b32_e32 v157, v153
	global_load_lds_dwordx4 v[2:3], off
	s_add_i32 m0, s33, 0x1a000
	v_lshl_add_u64 v[2:3], s[6:7], 0, v[156:157]
	s_add_u32 s6, s24, 0x4000
	s_addc_u32 s7, s25, 0
	s_add_i32 s38, s33, 0x8000
	s_add_i32 s39, s33, 0xa000
	global_load_lds_dwordx4 v[2:3], off
	v_lshl_add_u64 v[2:3], s[6:7], 0, v[152:153]
	s_mov_b32 m0, s38
	s_add_u32 s4, s4, 0x4000
	global_load_lds_dwordx4 v[2:3], off
	v_lshl_add_u64 v[2:3], s[6:7], 0, v[156:157]
	s_mov_b32 m0, s39
	s_addc_u32 s5, s5, 0
	global_load_lds_dwordx4 v[2:3], off
	s_add_i32 m0, s33, 0x1c000
	v_lshl_add_u64 v[2:3], s[4:5], 0, v[152:153]
	global_load_lds_dwordx4 v[2:3], off
	v_lshl_add_u64 v[2:3], s[4:5], 0, v[156:157]
	s_add_i32 m0, s33, 0x1e000
	v_readlane_b32 s4, v254, 38
	global_load_lds_dwordx4 v[2:3], off
	v_lshrrev_b32_e32 v1, 1, v0
	s_ashr_i32 s41, s4, 31
	v_readlane_b32 s4, v253, 19
	v_and_b32_e32 v1, 24, v1
	s_add_i32 s40, s28, -2
	s_ashr_i32 s42, s4, 31
	v_and_b32_e32 v206, 15, v0
	v_lshlrev_b32_e32 v2, 1, v1
	v_lshlrev_b32_e32 v0, 2, v0
	s_add_u32 s43, s12, s0
	v_lshl_or_b32 v2, v206, 6, v2
	v_and_b32_e32 v0, 32, v0
	s_waitcnt vmcnt(6)
	s_barrier
	s_waitcnt vmcnt(6)
	s_addc_u32 s44, s13, s1
	v_bitop3_b32 v3, v2, s20, v0 bitop3:0xde
	s_cmp_lg_u64 s[14:15], 0
	v_bitop3_b32 v207, v2, s26, v0 bitop3:0xde
	s_cselect_b64 s[12:13], -1, 0
	v_or_b32_e32 v208, s21, v1
	v_lshl_add_u64 v[158:159], s[52:53], 0, v[152:153]
	v_lshl_add_u64 v[160:161], s[52:53], 0, v[156:157]
	s_mov_b32 s45, 0
	v_add_u32_e32 v209, 0, v3
	s_barrier
	s_branch .LBB0_176

; #define PG8_STAGE(bufoff, gbase, voff) do { _Pragma("unroll") for (int _i = 0; _i < 2; ++_i) \
;         __builtin_amdgcn_global_load_lds((const unsigned*)((const char*)(gbase) + (voff)[_i]), (LAS unsigned*)(lds + (bufoff) + ldsw + _i * 8192), 16, 0, 0); } while (0)
; #define PG8_WAIT_V(n) asm volatile("s_waitcnt vmcnt(" #n ")" ::: "memory")
; #define PG8_BAR __builtin_amdgcn_s_barrier()
; template <class Epi>
; __device__ __forceinline__ void gemm_phase(LAS unsigned char* lds, const Gemm g, const StaticOrder& S, const Epi& E) {
;     ...
;     const char* cA = (const char*)g.A + (size_t)cur.pm * tstepA; const char* cB = (const char*)g.Bt + (size_t)cur.pn * tstepB;
;     PG8_STAGE(PG8_SB(0, 0), cB, voffB); PG8_STAGE(PG8_SA(0, 0), cA, voffA); PG8_STAGE(PG8_SB(0, 1), cB + hstepB, voffB); PG8_STAGE(PG8_SA(0, 1), cA + hstepA, voffA);
;     if (wr == 1) PG8_BAR;
;     PG8_WAIT_V(4); PG8_BAR;
;     PG8_STAGE(PG8_SB(1, 0), cB + kstep, voffB); PG8_STAGE(PG8_SA(1, 0), cA + kstep, voffA); PG8_STAGE(PG8_SB(1, 1), cB + hstepB + kstep, voffB);
;     PG8_WAIT_V(6); PG8_BAR;
.LBB0_242:
	s_and_b32 s4, s2, 3
	s_lshl_b32 s5, s1, 13
	s_lshl_b32 s6, s4, 12
	s_add_u32 s2, s14, 0x4000
	v_mov_b32_e32 v157, v153
	s_addc_u32 s3, s15, 0
	s_add_i32 m0, s25, 0x18000
	v_lshl_add_u64 v[2:3], s[2:3], 0, v[156:157]
	v_mov_b32_e32 v159, v153
	global_load_lds_dwordx4 v[2:3], off
	s_add_i32 m0, s25, 0x1a000
	v_lshl_add_u64 v[2:3], s[2:3], 0, v[158:159]
	s_add_u32 s2, s12, 0x4000
	s_addc_u32 s3, s13, 0
	s_add_i32 s29, s25, 0x8000
	global_load_lds_dwordx4 v[2:3], off
	v_lshl_add_u64 v[2:3], s[2:3], 0, v[156:157]
	s_mov_b32 m0, s29
	s_add_i32 s30, s25, 0xa000
	global_load_lds_dwordx4 v[2:3], off
	v_lshl_add_u64 v[2:3], s[2:3], 0, v[158:159]
	s_add_u32 s2, s14, 0x84000
	s_mov_b32 m0, s30
	s_addc_u32 s3, s15, 0
	global_load_lds_dwordx4 v[2:3], off
	s_add_i32 m0, s25, 0x1c000
	v_lshl_add_u64 v[2:3], s[2:3], 0, v[156:157]
	global_load_lds_dwordx4 v[2:3], off
	v_lshl_add_u64 v[2:3], s[2:3], 0, v[158:159]
	s_add_i32 m0, s25, 0x1e000
	v_and_b32_e32 v1, 15, v0
	global_load_lds_dwordx4 v[2:3], off
	v_bfe_u32 v2, v0, 4, 2
	v_lshlrev_b32_e32 v3, 4, v2
	v_lshlrev_b32_e32 v0, 2, v0
	v_lshl_or_b32 v165, s1, 6, v1
	v_lshl_or_b32 v1, v1, 6, v3
	v_and_b32_e32 v0, 32, v0
	s_sext_i32_i8 s34, s0
	v_bitop3_b32 v3, v1, s5, v0 bitop3:0xde
	v_bitop3_b32 v170, v1, s6, v0 bitop3:0xde
	v_lshlrev_b32_e32 v0, 2, v2
	v_readlane_b32 s0, v254, 38
	v_lshl_or_b32 v171, s4, 4, v0
	s_ashr_i32 s31, s0, 31
	v_readlane_b32 s0, v253, 3
	v_lshlrev_b32_e32 v152, 2, v171
	v_readlane_b32 s1, v253, 4
	s_waitcnt vmcnt(6)
	s_barrier
	s_waitcnt vmcnt(6)
	s_mov_b32 s33, 0
	v_add_u32_e32 v172, 0, v3
	v_lshl_add_u64 v[160:161], s[0:1], 0, v[152:153]
	v_readlane_b32 s0, v253, 5
	v_readlane_b32 s1, v253, 6
	s_barrier
	s_nop 0
	v_lshl_add_u64 v[162:163], s[0:1], 0, v[152:153]
	s_branch .LBB0_244
